# speedup vs baseline: 1.0067x; 1.0067x over previous
.Lgemm_noprio:
.LBB0_187:
	s_add_u32 m0, s35, 0xc000
	ds_read_b128 v[176:179], v164
	ds_read_b128 v[180:183], v164 offset:1024
	ds_read_b128 v[184:187], v164 offset:2048
	ds_read_b128 v[188:191], v164 offset:3072
	ds_read_b128 v[192:195], v162
	ds_read_b128 v[196:199], v162 offset:1024
	ds_read_b128 v[200:203], v162 offset:2048
	ds_read_b128 v[204:207], v162 offset:3072
	ds_read_b128 v[208:211], v162 offset:4096
	ds_read_b128 v[212:215], v162 offset:5120
	ds_read_b128 v[216:219], v162 offset:6144
	ds_read_b128 v[220:223], v162 offset:7168
	global_load_lds_dwordx4 v128, s[76:77]
	s_add_u32 m0, s35, 0xe000
	s_nop 0
	global_load_lds_dwordx4 v130, s[76:77]
	s_add_u32 s76, s76, 0x80
	s_addc_u32 s77, s77, 0
	s_waitcnt lgkmcnt(8)
	s_barrier
	s_waitcnt lgkmcnt(0)
	v_mfma_f32_16x16x32_bf16 v[124:127], v[176:179], v[192:195], v[124:127]
	v_mfma_f32_16x16x32_bf16 v[120:123], v[184:187], v[192:195], v[120:123]
	v_mfma_f32_16x16x32_bf16 v[116:119], v[176:179], v[200:203], v[116:119]
	v_mfma_f32_16x16x32_bf16 v[112:115], v[184:187], v[200:203], v[112:115]
	v_mfma_f32_16x16x32_bf16 v[108:111], v[176:179], v[208:211], v[108:111]
	v_mfma_f32_16x16x32_bf16 v[104:107], v[184:187], v[208:211], v[104:107]
	v_mfma_f32_16x16x32_bf16 v[100:103], v[176:179], v[216:219], v[100:103]
	v_mfma_f32_16x16x32_bf16 v[96:99], v[184:187], v[216:219], v[96:99]
	v_mfma_f32_16x16x32_bf16 v[124:127], v[180:183], v[196:199], v[124:127]
	v_mfma_f32_16x16x32_bf16 v[120:123], v[188:191], v[196:199], v[120:123]
	v_mfma_f32_16x16x32_bf16 v[116:119], v[180:183], v[204:207], v[116:119]
	v_mfma_f32_16x16x32_bf16 v[112:115], v[188:191], v[204:207], v[112:115]
	v_mfma_f32_16x16x32_bf16 v[108:111], v[180:183], v[212:215], v[108:111]
	v_mfma_f32_16x16x32_bf16 v[104:107], v[188:191], v[212:215], v[104:107]
	v_mfma_f32_16x16x32_bf16 v[100:103], v[180:183], v[220:223], v[100:103]
	v_mfma_f32_16x16x32_bf16 v[96:99], v[188:191], v[220:223], v[96:99]
	s_barrier
	s_add_u32 m0, s35, 0x10000
	ds_read_b128 v[224:227], v164 offset:16384
	ds_read_b128 v[228:231], v164 offset:17408
	ds_read_b128 v[232:235], v164 offset:18432
	ds_read_b128 v[236:239], v164 offset:19456
	global_load_lds_dwordx4 v128, s[42:43]
	s_add_u32 m0, s35, 0x12000
	s_nop 0
	global_load_lds_dwordx4 v130, s[42:43]
	s_add_u32 s42, s42, 0x80
	s_addc_u32 s43, s43, 0
	s_add_i32 s34, s34, 2
	s_barrier
	s_waitcnt lgkmcnt(0)
	v_mfma_f32_16x16x32_bf16 v[92:95], v[224:227], v[192:195], v[92:95]
	v_mfma_f32_16x16x32_bf16 v[88:91], v[232:235], v[192:195], v[88:91]
	v_mfma_f32_16x16x32_bf16 v[84:87], v[224:227], v[200:203], v[84:87]
	v_mfma_f32_16x16x32_bf16 v[80:83], v[232:235], v[200:203], v[80:83]
	v_mfma_f32_16x16x32_bf16 v[76:79], v[224:227], v[208:211], v[76:79]
	v_mfma_f32_16x16x32_bf16 v[72:75], v[232:235], v[208:211], v[72:75]
	v_mfma_f32_16x16x32_bf16 v[68:71], v[224:227], v[216:219], v[68:71]
	v_mfma_f32_16x16x32_bf16 v[64:67], v[232:235], v[216:219], v[64:67]
	v_mfma_f32_16x16x32_bf16 v[92:95], v[228:231], v[196:199], v[92:95]
	v_mfma_f32_16x16x32_bf16 v[88:91], v[236:239], v[196:199], v[88:91]
	v_mfma_f32_16x16x32_bf16 v[84:87], v[228:231], v[204:207], v[84:87]
	v_mfma_f32_16x16x32_bf16 v[80:83], v[236:239], v[204:207], v[80:83]
	v_mfma_f32_16x16x32_bf16 v[76:79], v[228:231], v[212:215], v[76:79]
	v_mfma_f32_16x16x32_bf16 v[72:75], v[236:239], v[212:215], v[72:75]
	v_mfma_f32_16x16x32_bf16 v[68:71], v[228:231], v[220:223], v[68:71]
	v_mfma_f32_16x16x32_bf16 v[64:67], v[236:239], v[220:223], v[64:67]
	s_barrier
	s_add_u32 m0, s35, 0x0
	ds_read_b128 v[192:195], v162 offset:16384
	ds_read_b128 v[196:199], v162 offset:17408
	ds_read_b128 v[200:203], v162 offset:18432
	ds_read_b128 v[204:207], v162 offset:19456
	ds_read_b128 v[208:211], v162 offset:20480
	ds_read_b128 v[212:215], v162 offset:21504
	ds_read_b128 v[216:219], v162 offset:22528
	ds_read_b128 v[220:223], v162 offset:23552
	global_load_lds_dwordx4 v128, s[72:73]
	s_add_u32 m0, s35, 0x2000
	s_nop 0
	global_load_lds_dwordx4 v130, s[72:73]
	s_add_u32 s72, s72, 0x80
	s_addc_u32 s73, s73, 0
	s_barrier
	s_waitcnt lgkmcnt(0)
	v_mfma_f32_16x16x32_bf16 v[60:63], v[176:179], v[192:195], v[60:63]
	v_mfma_f32_16x16x32_bf16 v[56:59], v[184:187], v[192:195], v[56:59]
	v_mfma_f32_16x16x32_bf16 v[52:55], v[176:179], v[200:203], v[52:55]
	v_mfma_f32_16x16x32_bf16 v[48:51], v[184:187], v[200:203], v[48:51]
	v_mfma_f32_16x16x32_bf16 v[44:47], v[176:179], v[208:211], v[44:47]
	v_mfma_f32_16x16x32_bf16 v[40:43], v[184:187], v[208:211], v[40:43]
	v_mfma_f32_16x16x32_bf16 v[36:39], v[176:179], v[216:219], v[36:39]
	v_mfma_f32_16x16x32_bf16 v[32:35], v[184:187], v[216:219], v[32:35]
	v_mfma_f32_16x16x32_bf16 v[60:63], v[180:183], v[196:199], v[60:63]
	v_mfma_f32_16x16x32_bf16 v[56:59], v[188:191], v[196:199], v[56:59]
	v_mfma_f32_16x16x32_bf16 v[52:55], v[180:183], v[204:207], v[52:55]
	v_mfma_f32_16x16x32_bf16 v[48:51], v[188:191], v[204:207], v[48:51]
	v_mfma_f32_16x16x32_bf16 v[44:47], v[180:183], v[212:215], v[44:47]
	v_mfma_f32_16x16x32_bf16 v[40:43], v[188:191], v[212:215], v[40:43]
	v_mfma_f32_16x16x32_bf16 v[36:39], v[180:183], v[220:223], v[36:39]
	v_mfma_f32_16x16x32_bf16 v[32:35], v[188:191], v[220:223], v[32:35]
	s_barrier
	s_add_u32 m0, s35, 0x14000
	s_nop 0
	global_load_lds_dwordx4 v128, s[78:79]
	s_add_u32 m0, s35, 0x16000
	s_nop 0
	global_load_lds_dwordx4 v130, s[78:79]
	s_add_u32 s78, s78, 0x80
	s_addc_u32 s79, s79, 0
	s_waitcnt vmcnt(6)
	s_barrier
	v_mfma_f32_16x16x32_bf16 v[28:31], v[224:227], v[192:195], v[28:31]
	v_mfma_f32_16x16x32_bf16 v[24:27], v[232:235], v[192:195], v[24:27]
	v_mfma_f32_16x16x32_bf16 v[20:23], v[224:227], v[200:203], v[20:23]
	v_mfma_f32_16x16x32_bf16 v[16:19], v[232:235], v[200:203], v[16:19]
	v_mfma_f32_16x16x32_bf16 v[12:15], v[224:227], v[208:211], v[12:15]
	v_mfma_f32_16x16x32_bf16 v[8:11], v[232:235], v[208:211], v[8:11]
	v_mfma_f32_16x16x32_bf16 v[4:7], v[224:227], v[216:219], v[4:7]
	v_mfma_f32_16x16x32_bf16 v[0:3], v[232:235], v[216:219], v[0:3]
	v_mfma_f32_16x16x32_bf16 v[28:31], v[228:231], v[196:199], v[28:31]
	v_mfma_f32_16x16x32_bf16 v[24:27], v[236:239], v[196:199], v[24:27]
	v_mfma_f32_16x16x32_bf16 v[20:23], v[228:231], v[204:207], v[20:23]
	v_mfma_f32_16x16x32_bf16 v[16:19], v[236:239], v[204:207], v[16:19]
	v_mfma_f32_16x16x32_bf16 v[12:15], v[228:231], v[212:215], v[12:15]
	v_mfma_f32_16x16x32_bf16 v[8:11], v[236:239], v[212:215], v[8:11]
	v_mfma_f32_16x16x32_bf16 v[4:7], v[228:231], v[220:223], v[4:7]
	v_mfma_f32_16x16x32_bf16 v[0:3], v[236:239], v[220:223], v[0:3]
	s_barrier
	s_add_u32 m0, s35, 0x4000
	ds_read_b128 v[176:179], v164 offset:32768
	ds_read_b128 v[180:183], v164 offset:33792
	ds_read_b128 v[184:187], v164 offset:34816
	ds_read_b128 v[188:191], v164 offset:35840
	ds_read_b128 v[192:195], v162 offset:32768
	ds_read_b128 v[196:199], v162 offset:33792
	ds_read_b128 v[200:203], v162 offset:34816
	ds_read_b128 v[204:207], v162 offset:35840
	ds_read_b128 v[208:211], v162 offset:36864
	ds_read_b128 v[212:215], v162 offset:37888
	ds_read_b128 v[216:219], v162 offset:38912
	ds_read_b128 v[220:223], v162 offset:39936
	global_load_lds_dwordx4 v128, s[76:77]
	s_add_u32 m0, s35, 0x6000
	s_nop 0
	global_load_lds_dwordx4 v130, s[76:77]
	s_add_u32 s76, s76, 0x80
	s_addc_u32 s77, s77, 0
	s_waitcnt lgkmcnt(8)
	s_barrier
	s_waitcnt lgkmcnt(0)
	v_mfma_f32_16x16x32_bf16 v[124:127], v[176:179], v[192:195], v[124:127]
	v_mfma_f32_16x16x32_bf16 v[120:123], v[184:187], v[192:195], v[120:123]
	v_mfma_f32_16x16x32_bf16 v[116:119], v[176:179], v[200:203], v[116:119]
	v_mfma_f32_16x16x32_bf16 v[112:115], v[184:187], v[200:203], v[112:115]
	v_mfma_f32_16x16x32_bf16 v[108:111], v[176:179], v[208:211], v[108:111]
	v_mfma_f32_16x16x32_bf16 v[104:107], v[184:187], v[208:211], v[104:107]
	v_mfma_f32_16x16x32_bf16 v[100:103], v[176:179], v[216:219], v[100:103]
	v_mfma_f32_16x16x32_bf16 v[96:99], v[184:187], v[216:219], v[96:99]
	v_mfma_f32_16x16x32_bf16 v[124:127], v[180:183], v[196:199], v[124:127]
	v_mfma_f32_16x16x32_bf16 v[120:123], v[188:191], v[196:199], v[120:123]
	v_mfma_f32_16x16x32_bf16 v[116:119], v[180:183], v[204:207], v[116:119]
	v_mfma_f32_16x16x32_bf16 v[112:115], v[188:191], v[204:207], v[112:115]
	v_mfma_f32_16x16x32_bf16 v[108:111], v[180:183], v[212:215], v[108:111]
	v_mfma_f32_16x16x32_bf16 v[104:107], v[188:191], v[212:215], v[104:107]
	v_mfma_f32_16x16x32_bf16 v[100:103], v[180:183], v[220:223], v[100:103]
	v_mfma_f32_16x16x32_bf16 v[96:99], v[188:191], v[220:223], v[96:99]
	s_barrier
	s_add_u32 m0, s35, 0x18000
	ds_read_b128 v[224:227], v164 offset:49152
	ds_read_b128 v[228:231], v164 offset:50176
	ds_read_b128 v[232:235], v164 offset:51200
	ds_read_b128 v[236:239], v164 offset:52224
	global_load_lds_dwordx4 v128, s[42:43]
	s_add_u32 m0, s35, 0x1a000
	s_nop 0
	global_load_lds_dwordx4 v130, s[42:43]
	s_add_u32 s42, s42, 0x80
	s_addc_u32 s43, s43, 0
	s_barrier
	s_waitcnt lgkmcnt(0)
	v_mfma_f32_16x16x32_bf16 v[92:95], v[224:227], v[192:195], v[92:95]
	v_mfma_f32_16x16x32_bf16 v[88:91], v[232:235], v[192:195], v[88:91]
	v_mfma_f32_16x16x32_bf16 v[84:87], v[224:227], v[200:203], v[84:87]
	v_mfma_f32_16x16x32_bf16 v[80:83], v[232:235], v[200:203], v[80:83]
	v_mfma_f32_16x16x32_bf16 v[76:79], v[224:227], v[208:211], v[76:79]
	v_mfma_f32_16x16x32_bf16 v[72:75], v[232:235], v[208:211], v[72:75]
	v_mfma_f32_16x16x32_bf16 v[68:71], v[224:227], v[216:219], v[68:71]
	v_mfma_f32_16x16x32_bf16 v[64:67], v[232:235], v[216:219], v[64:67]
	v_mfma_f32_16x16x32_bf16 v[92:95], v[228:231], v[196:199], v[92:95]
	v_mfma_f32_16x16x32_bf16 v[88:91], v[236:239], v[196:199], v[88:91]
	v_mfma_f32_16x16x32_bf16 v[84:87], v[228:231], v[204:207], v[84:87]
	v_mfma_f32_16x16x32_bf16 v[80:83], v[236:239], v[204:207], v[80:83]
	v_mfma_f32_16x16x32_bf16 v[76:79], v[228:231], v[212:215], v[76:79]
	v_mfma_f32_16x16x32_bf16 v[72:75], v[236:239], v[212:215], v[72:75]
	v_mfma_f32_16x16x32_bf16 v[68:71], v[228:231], v[220:223], v[68:71]
	v_mfma_f32_16x16x32_bf16 v[64:67], v[236:239], v[220:223], v[64:67]
	s_barrier
	s_add_u32 m0, s35, 0x8000
	ds_read_b128 v[192:195], v162 offset:49152
	ds_read_b128 v[196:199], v162 offset:50176
	ds_read_b128 v[200:203], v162 offset:51200
	ds_read_b128 v[204:207], v162 offset:52224
	ds_read_b128 v[208:211], v162 offset:53248
	ds_read_b128 v[212:215], v162 offset:54272
	ds_read_b128 v[216:219], v162 offset:55296
	ds_read_b128 v[220:223], v162 offset:56320
	global_load_lds_dwordx4 v128, s[72:73]
	s_add_u32 m0, s35, 0xa000
	s_nop 0
	global_load_lds_dwordx4 v130, s[72:73]
	s_add_u32 s72, s72, 0x80
	s_addc_u32 s73, s73, 0
	s_barrier
	s_waitcnt lgkmcnt(0)
	v_mfma_f32_16x16x32_bf16 v[60:63], v[176:179], v[192:195], v[60:63]
	v_mfma_f32_16x16x32_bf16 v[56:59], v[184:187], v[192:195], v[56:59]
	v_mfma_f32_16x16x32_bf16 v[52:55], v[176:179], v[200:203], v[52:55]
	v_mfma_f32_16x16x32_bf16 v[48:51], v[184:187], v[200:203], v[48:51]
	v_mfma_f32_16x16x32_bf16 v[44:47], v[176:179], v[208:211], v[44:47]
	v_mfma_f32_16x16x32_bf16 v[40:43], v[184:187], v[208:211], v[40:43]
	v_mfma_f32_16x16x32_bf16 v[36:39], v[176:179], v[216:219], v[36:39]
	v_mfma_f32_16x16x32_bf16 v[32:35], v[184:187], v[216:219], v[32:35]
	v_mfma_f32_16x16x32_bf16 v[60:63], v[180:183], v[196:199], v[60:63]
	v_mfma_f32_16x16x32_bf16 v[56:59], v[188:191], v[196:199], v[56:59]
	v_mfma_f32_16x16x32_bf16 v[52:55], v[180:183], v[204:207], v[52:55]
	v_mfma_f32_16x16x32_bf16 v[48:51], v[188:191], v[204:207], v[48:51]
	v_mfma_f32_16x16x32_bf16 v[44:47], v[180:183], v[212:215], v[44:47]
	v_mfma_f32_16x16x32_bf16 v[40:43], v[188:191], v[212:215], v[40:43]
	v_mfma_f32_16x16x32_bf16 v[36:39], v[180:183], v[220:223], v[36:39]
	v_mfma_f32_16x16x32_bf16 v[32:35], v[188:191], v[220:223], v[32:35]
	s_barrier
	s_add_u32 m0, s35, 0x1c000
	s_nop 0
	global_load_lds_dwordx4 v128, s[78:79]
	s_add_u32 m0, s35, 0x1e000
	s_nop 0
	global_load_lds_dwordx4 v130, s[78:79]
	s_add_u32 s78, s78, 0x80
	s_addc_u32 s79, s79, 0
	s_waitcnt vmcnt(6)
	s_barrier
	v_mfma_f32_16x16x32_bf16 v[28:31], v[224:227], v[192:195], v[28:31]
	v_mfma_f32_16x16x32_bf16 v[24:27], v[232:235], v[192:195], v[24:27]
	v_mfma_f32_16x16x32_bf16 v[20:23], v[224:227], v[200:203], v[20:23]
	v_mfma_f32_16x16x32_bf16 v[16:19], v[232:235], v[200:203], v[16:19]
	v_mfma_f32_16x16x32_bf16 v[12:15], v[224:227], v[208:211], v[12:15]
	v_mfma_f32_16x16x32_bf16 v[8:11], v[232:235], v[208:211], v[8:11]
	v_mfma_f32_16x16x32_bf16 v[4:7], v[224:227], v[216:219], v[4:7]
	v_mfma_f32_16x16x32_bf16 v[0:3], v[232:235], v[216:219], v[0:3]
	v_mfma_f32_16x16x32_bf16 v[28:31], v[228:231], v[196:199], v[28:31]
	v_mfma_f32_16x16x32_bf16 v[24:27], v[236:239], v[196:199], v[24:27]
	v_mfma_f32_16x16x32_bf16 v[20:23], v[228:231], v[204:207], v[20:23]
	v_mfma_f32_16x16x32_bf16 v[16:19], v[236:239], v[204:207], v[16:19]
	v_mfma_f32_16x16x32_bf16 v[12:15], v[228:231], v[212:215], v[12:15]
	v_mfma_f32_16x16x32_bf16 v[8:11], v[236:239], v[212:215], v[8:11]
	v_mfma_f32_16x16x32_bf16 v[4:7], v[228:231], v[220:223], v[4:7]
	v_mfma_f32_16x16x32_bf16 v[0:3], v[236:239], v[220:223], v[0:3]
	s_cmp_lt_u32 s34, s3
	s_barrier
	s_cbranch_scc1 .LBB0_187
	s_mov_b64 s[72:73], 0x80
	s_mov_b64 s[76:77], 0x100
	s_mov_b64 s[78:79], 0x180
	s_add_i32 s66, s2, -1
	s_lshl_b64 s[2:3], s[66:67], 7
	s_add_u32 s2, s54, s2
	s_addc_u32 s3, s55, s3
	v_readfirstlane_b32 s34, v174
	v_lshl_add_u64 v[150:151], s[2:3], 0, v[128:129]
	s_mov_b32 m0, s34
	v_lshl_add_u64 v[130:131], s[2:3], 0, v[130:131]
	v_readfirstlane_b32 s2, v175
	ds_read_b128 v[132:135], v164
	ds_read_b128 v[136:139], v164 offset:1024
	ds_read_b128 v[140:143], v164 offset:2048
	ds_read_b128 v[144:147], v164 offset:3072
	ds_read_b128 v[158:161], v162
	ds_read_b128 v[166:169], v162 offset:1024
	ds_read_b128 v[170:173], v162 offset:2048
	ds_read_b128 v[176:179], v162 offset:3072
	ds_read_b128 v[180:183], v162 offset:4096
	ds_read_b128 v[184:187], v162 offset:5120
	ds_read_b128 v[188:191], v162 offset:6144
	ds_read_b128 v[192:195], v162 offset:7168
	global_load_lds_dwordx4 v[150:151], off
	s_mov_b32 m0, s2
	s_nop 0
	global_load_lds_dwordx4 v[130:131], off
	s_barrier
	s_waitcnt lgkmcnt(0)
	s_waitcnt lgkmcnt(0)
	v_mfma_f32_16x16x32_bf16 v[124:127], v[132:135], v[158:161], v[124:127]
	v_mfma_f32_16x16x32_bf16 v[120:123], v[140:143], v[158:161], v[120:123]
	v_mfma_f32_16x16x32_bf16 v[116:119], v[132:135], v[170:173], v[116:119]
	v_mfma_f32_16x16x32_bf16 v[112:115], v[140:143], v[170:173], v[112:115]
	v_mfma_f32_16x16x32_bf16 v[100:103], v[132:135], v[188:191], v[100:103]
	v_mfma_f32_16x16x32_bf16 v[96:99], v[140:143], v[188:191], v[96:99]
	v_mfma_f32_16x16x32_bf16 v[124:127], v[136:139], v[166:169], v[124:127]
	v_mfma_f32_16x16x32_bf16 v[120:123], v[144:147], v[166:169], v[120:123]
	v_mfma_f32_16x16x32_bf16 v[116:119], v[136:139], v[176:179], v[116:119]
	v_mfma_f32_16x16x32_bf16 v[112:115], v[144:147], v[176:179], v[112:115]
	v_mfma_f32_16x16x32_bf16 v[108:111], v[132:135], v[180:183], v[108:111]
	v_mfma_f32_16x16x32_bf16 v[104:107], v[140:143], v[180:183], v[104:107]
	v_mfma_f32_16x16x32_bf16 v[100:103], v[136:139], v[192:195], v[100:103]
	v_mfma_f32_16x16x32_bf16 v[96:99], v[144:147], v[192:195], v[96:99]
	v_mfma_f32_16x16x32_bf16 v[196:199], v[136:139], v[184:187], v[108:111]
	v_mfma_f32_16x16x32_bf16 v[200:203], v[144:147], v[184:187], v[104:107]
	s_barrier
	s_nop 1
	ds_read_b128 v[104:107], v164 offset:16384
	ds_read_b128 v[108:111], v164 offset:17408
	ds_read_b128 v[204:207], v164 offset:18432
	ds_read_b128 v[208:211], v164 offset:19456
	s_barrier
	s_waitcnt lgkmcnt(0)
	s_waitcnt lgkmcnt(0)
	v_mfma_f32_16x16x32_bf16 v[84:87], v[104:107], v[170:173], v[84:87]
	v_mfma_f32_16x16x32_bf16 v[80:83], v[204:207], v[170:173], v[80:83]
	v_mfma_f32_16x16x32_bf16 v[68:71], v[104:107], v[188:191], v[68:71]
	v_mfma_f32_16x16x32_bf16 v[64:67], v[204:207], v[188:191], v[64:67]
	v_mfma_f32_16x16x32_bf16 v[92:95], v[104:107], v[158:161], v[92:95]
	v_mfma_f32_16x16x32_bf16 v[88:91], v[204:207], v[158:161], v[88:91]
	v_mfma_f32_16x16x32_bf16 v[84:87], v[108:111], v[176:179], v[84:87]
	v_mfma_f32_16x16x32_bf16 v[80:83], v[208:211], v[176:179], v[80:83]
	v_mfma_f32_16x16x32_bf16 v[76:79], v[104:107], v[180:183], v[76:79]
	v_mfma_f32_16x16x32_bf16 v[72:75], v[204:207], v[180:183], v[72:75]
	v_mfma_f32_16x16x32_bf16 v[68:71], v[108:111], v[192:195], v[68:71]
	v_mfma_f32_16x16x32_bf16 v[64:67], v[208:211], v[192:195], v[64:67]
	v_mfma_f32_16x16x32_bf16 v[212:215], v[108:111], v[166:169], v[92:95]
	v_mfma_f32_16x16x32_bf16 v[158:161], v[208:211], v[166:169], v[88:91]
	v_mfma_f32_16x16x32_bf16 v[166:169], v[108:111], v[184:187], v[76:79]
	v_mfma_f32_16x16x32_bf16 v[170:173], v[208:211], v[184:187], v[72:75]
	s_barrier
	s_nop 0
	ds_read_b128 v[72:75], v162 offset:16384
	ds_read_b128 v[76:79], v162 offset:17408
	ds_read_b128 v[88:91], v162 offset:18432
	ds_read_b128 v[92:95], v162 offset:19456
	ds_read_b128 v[174:177], v162 offset:20480
	ds_read_b128 v[178:181], v162 offset:21504
	ds_read_b128 v[182:185], v162 offset:22528
	ds_read_b128 v[186:189], v162 offset:23552
	s_waitcnt vmcnt(4)
	s_barrier
	s_waitcnt lgkmcnt(0)
	s_waitcnt lgkmcnt(0)
	v_mfma_f32_16x16x32_bf16 v[60:63], v[132:135], v[72:75], v[60:63]
	v_mfma_f32_16x16x32_bf16 v[56:59], v[140:143], v[72:75], v[56:59]
	v_mfma_f32_16x16x32_bf16 v[52:55], v[132:135], v[88:91], v[52:55]
	v_mfma_f32_16x16x32_bf16 v[48:51], v[140:143], v[88:91], v[48:51]
	v_mfma_f32_16x16x32_bf16 v[36:39], v[132:135], v[182:185], v[36:39]
	v_mfma_f32_16x16x32_bf16 v[32:35], v[140:143], v[182:185], v[32:35]
	v_mfma_f32_16x16x32_bf16 v[60:63], v[136:139], v[76:79], v[60:63]
	v_mfma_f32_16x16x32_bf16 v[56:59], v[144:147], v[76:79], v[56:59]
	v_mfma_f32_16x16x32_bf16 v[52:55], v[136:139], v[92:95], v[52:55]
	v_mfma_f32_16x16x32_bf16 v[48:51], v[144:147], v[92:95], v[48:51]
	v_mfma_f32_16x16x32_bf16 v[44:47], v[132:135], v[174:177], v[44:47]
	v_mfma_f32_16x16x32_bf16 v[40:43], v[140:143], v[174:177], v[40:43]
	v_mfma_f32_16x16x32_bf16 v[36:39], v[136:139], v[186:189], v[36:39]
	v_mfma_f32_16x16x32_bf16 v[32:35], v[144:147], v[186:189], v[32:35]
	v_mfma_f32_16x16x32_bf16 v[190:193], v[136:139], v[178:181], v[44:47]
	v_mfma_f32_16x16x32_bf16 v[216:219], v[144:147], v[178:181], v[40:43]
	v_mfma_f32_16x16x32_bf16 v[20:23], v[104:107], v[88:91], v[20:23]
	v_mfma_f32_16x16x32_bf16 v[16:19], v[204:207], v[88:91], v[16:19]
	v_mfma_f32_16x16x32_bf16 v[4:7], v[104:107], v[182:185], v[4:7]
	v_mfma_f32_16x16x32_bf16 v[0:3], v[204:207], v[182:185], v[0:3]
	v_mfma_f32_16x16x32_bf16 v[28:31], v[104:107], v[72:75], v[28:31]
	v_mfma_f32_16x16x32_bf16 v[24:27], v[204:207], v[72:75], v[24:27]
	v_mfma_f32_16x16x32_bf16 v[20:23], v[108:111], v[92:95], v[20:23]
	v_mfma_f32_16x16x32_bf16 v[16:19], v[208:211], v[92:95], v[16:19]
	v_mfma_f32_16x16x32_bf16 v[12:15], v[104:107], v[174:177], v[12:15]
	v_mfma_f32_16x16x32_bf16 v[8:11], v[204:207], v[174:177], v[8:11]
	v_mfma_f32_16x16x32_bf16 v[4:7], v[108:111], v[186:189], v[4:7]
	v_mfma_f32_16x16x32_bf16 v[0:3], v[208:211], v[186:189], v[0:3]
	v_mfma_f32_16x16x32_bf16 v[130:133], v[108:111], v[76:79], v[28:31]
	v_mfma_f32_16x16x32_bf16 v[134:137], v[208:211], v[76:79], v[24:27]
	v_mfma_f32_16x16x32_bf16 v[138:141], v[108:111], v[178:181], v[12:15]
	v_mfma_f32_16x16x32_bf16 v[142:145], v[208:211], v[178:181], v[8:11]
	s_barrier
	s_nop 0
	ds_read_b128 v[8:11], v164 offset:32768
	ds_read_b128 v[12:15], v164 offset:33792
	ds_read_b128 v[174:177], v164 offset:34816
	ds_read_b128 v[178:181], v164 offset:35840
	ds_read_b128 v[24:27], v162 offset:32768
	ds_read_b128 v[28:31], v162 offset:33792
	ds_read_b128 v[40:43], v162 offset:34816
	ds_read_b128 v[44:47], v162 offset:35840
	ds_read_b128 v[182:185], v162 offset:36864
	ds_read_b128 v[186:189], v162 offset:37888
	ds_read_b128 v[204:207], v162 offset:38912
	ds_read_b128 v[208:211], v162 offset:39936
	s_waitcnt vmcnt(2)
	s_barrier
	s_waitcnt lgkmcnt(0)
	s_waitcnt lgkmcnt(0)
	v_mfma_f32_16x16x32_bf16 v[72:75], v[8:11], v[24:27], v[124:127]
	v_mfma_f32_16x16x32_bf16 v[124:127], v[12:15], v[28:31], v[72:75]
	v_mfma_f32_16x16x32_bf16 v[72:75], v[174:177], v[24:27], v[120:123]
	v_mfma_f32_16x16x32_bf16 v[120:123], v[178:181], v[28:31], v[72:75]
	v_mfma_f32_16x16x32_bf16 v[72:75], v[8:11], v[40:43], v[116:119]
	v_mfma_f32_16x16x32_bf16 v[108:111], v[12:15], v[44:47], v[72:75]
	v_mfma_f32_16x16x32_bf16 v[72:75], v[174:177], v[40:43], v[112:115]
	v_mfma_f32_16x16x32_bf16 v[104:107], v[178:181], v[44:47], v[72:75]
	v_mfma_f32_16x16x32_bf16 v[72:75], v[8:11], v[182:185], v[196:199]
	v_mfma_f32_16x16x32_bf16 v[92:95], v[12:15], v[186:189], v[72:75]
	v_mfma_f32_16x16x32_bf16 v[72:75], v[174:177], v[182:185], v[200:203]
	v_mfma_f32_16x16x32_bf16 v[88:91], v[178:181], v[186:189], v[72:75]
	v_mfma_f32_16x16x32_bf16 v[72:75], v[8:11], v[204:207], v[100:103]
	v_mfma_f32_16x16x32_bf16 v[76:79], v[12:15], v[208:211], v[72:75]
	v_mfma_f32_16x16x32_bf16 v[72:75], v[174:177], v[204:207], v[96:99]
	v_mfma_f32_16x16x32_bf16 v[72:75], v[178:181], v[208:211], v[72:75]
	s_barrier
	ds_read_b128 v[194:197], v164 offset:49152
	ds_read_b128 v[198:201], v164 offset:50176
	ds_read_b128 v[220:223], v164 offset:51200
	ds_read_b128 v[224:227], v164 offset:52224
	s_waitcnt vmcnt(0)
	s_barrier
	s_waitcnt lgkmcnt(0)
	s_waitcnt lgkmcnt(0)
	v_mfma_f32_16x16x32_bf16 v[96:99], v[194:197], v[24:27], v[212:215]
	v_mfma_f32_16x16x32_bf16 v[24:27], v[220:223], v[24:27], v[158:161]
	v_mfma_f32_16x16x32_bf16 v[112:115], v[224:227], v[28:31], v[24:27]
	v_mfma_f32_16x16x32_bf16 v[24:27], v[194:197], v[40:43], v[84:87]
	v_mfma_f32_16x16x32_bf16 v[100:103], v[198:201], v[44:47], v[24:27]
	v_mfma_f32_16x16x32_bf16 v[24:27], v[220:223], v[40:43], v[80:83]
	v_mfma_f32_16x16x32_bf16 v[116:119], v[198:201], v[28:31], v[96:99]
	v_mfma_f32_16x16x32_bf16 v[96:99], v[224:227], v[44:47], v[24:27]
	v_mfma_f32_16x16x32_bf16 v[24:27], v[194:197], v[182:185], v[166:169]
	v_mfma_f32_16x16x32_bf16 v[84:87], v[198:201], v[186:189], v[24:27]
	v_mfma_f32_16x16x32_bf16 v[24:27], v[220:223], v[182:185], v[170:173]
	v_mfma_f32_16x16x32_bf16 v[80:83], v[224:227], v[186:189], v[24:27]
	v_mfma_f32_16x16x32_bf16 v[24:27], v[194:197], v[204:207], v[68:71]
	v_mfma_f32_16x16x32_bf16 v[68:71], v[198:201], v[208:211], v[24:27]
	v_mfma_f32_16x16x32_bf16 v[24:27], v[220:223], v[204:207], v[64:67]
	v_mfma_f32_16x16x32_bf16 v[64:67], v[224:227], v[208:211], v[24:27]
	s_barrier
	ds_read_b128 v[158:161], v162 offset:49152
	ds_read_b128 v[164:167], v162 offset:50176
	ds_read_b128 v[168:171], v162 offset:51200
	ds_read_b128 v[182:185], v162 offset:52224
	ds_read_b128 v[186:189], v162 offset:53248
	ds_read_b128 v[202:205], v162 offset:54272
	ds_read_b128 v[206:209], v162 offset:55296
	ds_read_b128 v[210:213], v162 offset:56320
	s_barrier
	s_waitcnt lgkmcnt(0)
	s_waitcnt lgkmcnt(0)
	v_mfma_f32_16x16x32_bf16 v[24:27], v[8:11], v[158:161], v[60:63]
	v_mfma_f32_16x16x32_bf16 v[60:63], v[12:15], v[164:167], v[24:27]
	v_mfma_f32_16x16x32_bf16 v[24:27], v[174:177], v[158:161], v[56:59]
	v_mfma_f32_16x16x32_bf16 v[56:59], v[178:181], v[164:167], v[24:27]
	v_mfma_f32_16x16x32_bf16 v[24:27], v[8:11], v[168:171], v[52:55]
	v_mfma_f32_16x16x32_bf16 v[44:47], v[12:15], v[182:185], v[24:27]
	v_mfma_f32_16x16x32_bf16 v[24:27], v[174:177], v[168:171], v[48:51]
	v_mfma_f32_16x16x32_bf16 v[40:43], v[178:181], v[182:185], v[24:27]
	v_mfma_f32_16x16x32_bf16 v[24:27], v[8:11], v[186:189], v[190:193]
	v_mfma_f32_16x16x32_bf16 v[8:11], v[8:11], v[206:209], v[36:39]
	v_mfma_f32_16x16x32_bf16 v[28:31], v[12:15], v[202:205], v[24:27]
	v_mfma_f32_16x16x32_bf16 v[24:27], v[174:177], v[186:189], v[216:219]
	v_mfma_f32_16x16x32_bf16 v[12:15], v[12:15], v[210:213], v[8:11]
	v_mfma_f32_16x16x32_bf16 v[8:11], v[174:177], v[206:209], v[32:35]
	v_mfma_f32_16x16x32_bf16 v[24:27], v[178:181], v[202:205], v[24:27]
	v_mfma_f32_16x16x32_bf16 v[8:11], v[178:181], v[210:213], v[8:11]
	v_mfma_f32_16x16x32_bf16 v[32:35], v[194:197], v[158:161], v[130:133]
	v_mfma_f32_16x16x32_bf16 v[52:55], v[198:201], v[164:167], v[32:35]
	v_mfma_f32_16x16x32_bf16 v[32:35], v[220:223], v[158:161], v[134:137]
	v_mfma_f32_16x16x32_bf16 v[16:19], v[220:223], v[168:171], v[16:19]
	v_mfma_f32_16x16x32_bf16 v[48:51], v[224:227], v[164:167], v[32:35]
	v_mfma_f32_16x16x32_bf16 v[20:23], v[194:197], v[168:171], v[20:23]
	v_mfma_f32_16x16x32_bf16 v[32:35], v[224:227], v[182:185], v[16:19]
	v_mfma_f32_16x16x32_bf16 v[16:19], v[194:197], v[186:189], v[138:141]
	v_mfma_f32_16x16x32_bf16 v[36:39], v[198:201], v[182:185], v[20:23]
	v_mfma_f32_16x16x32_bf16 v[20:23], v[198:201], v[202:205], v[16:19]
	v_mfma_f32_16x16x32_bf16 v[16:19], v[220:223], v[186:189], v[142:145]
	v_mfma_f32_16x16x32_bf16 v[4:7], v[194:197], v[206:209], v[4:7]
	v_mfma_f32_16x16x32_bf16 v[0:3], v[220:223], v[206:209], v[0:3]
	v_mfma_f32_16x16x32_bf16 v[16:19], v[224:227], v[202:205], v[16:19]
	v_mfma_f32_16x16x32_bf16 v[4:7], v[198:201], v[210:213], v[4:7]
	v_mfma_f32_16x16x32_bf16 v[0:3], v[224:227], v[210:213], v[0:3]
	s_setprio 0
	s_movk_i32 s2, 0x100
	v_cmp_gt_u32_e32 vcc, s2, v157
	s_barrier
	s_and_saveexec_b64 s[2:3], vcc
	s_cbranch_execz .LBB0_190
	s_barrier
